# filter_norm partial-sum loop with 64 loads in flight per wait (same summation order)
# baseline (speedup 1.0000x reference)
; #define VBID ((int)blockIdx.x * 2 + vhalf())
; DEV void phase_filter_norm(const Params& p, char* smem) {
;     ...
;   for (int it = VBID; it < 512 + 1024; it += NVB) {
;     const int g = (it < 512) ? 0 : 1;
;     const int L = g ? 8192 : 4096;
;     const int li = g ? it - 512 : it;
;     const int ntt = L / 64;
;     const int ct = li / ntt, tt = li % ntt;
;     const long rowbase = g ? 4096 : 0;
;     const int prow0 = g ? 256 : 0, nprow = g ? 512 : 256;
;     u16* KK = (u16*)(p.ws + OFF_KK) + (g ? (size_t)512 * 8192 : 0);
;     __syncthreads();
;     {
;       const int c = tid & 63, ph = tid >> 6;
;       float s = 0.f;
; #pragma unroll 8
;       for (int r = ph; r < nprow; r += 4) {
;         s += part[(long)(prow0 + r) * 1024 + ct * 64 + c];
;         s += part[(long)(prow0 + r) * 1024 + 512 + ct * 64 + c];
;       }
;       red[ph * 64 + c] = s;
.LBB0_148:
	s_add_i32 s16, s20, 0xfffffe00
	s_cmpk_gt_i32 s20, 0x1ff
	s_cselect_b64 s[14:15], -1, 0
	s_and_b64 s[12:13], s[14:15], exec
	s_cselect_b32 s4, s24, 0x1000
	s_cselect_b32 s26, s16, s20
	s_cselect_b32 s28, 0x100, 0
	s_cselect_b32 s29, s25, 0x100
	s_lshr_b32 s27, s4, 6
	s_abs_i32 s12, s27
	v_cvt_f32_u32_e32 v2, s12
	s_sub_i32 s17, 0, s12
	s_abs_i32 s13, s26
	s_xor_b32 s16, s26, s27
	v_rcp_iflag_f32_e32 v2, v2
	s_ashr_i32 s16, s16, 31
	v_mov_b32_e32 v52, v0
	v_mov_b32_e32 v51, v3
	v_mul_f32_e32 v2, 0x4f7ffffe, v2
	v_cvt_u32_f32_e32 v2, v2
	s_barrier
	v_readfirstlane_b32 s18, v2
	s_mul_i32 s17, s17, s18
	s_mul_hi_u32 s17, s18, s17
	s_add_i32 s18, s18, s17
	s_mul_hi_u32 s17, s13, s18
	s_mul_i32 s18, s17, s12
	s_sub_i32 s13, s13, s18
	s_add_i32 s19, s17, 1
	s_sub_i32 s18, s13, s12
	s_cmp_ge_u32 s13, s12
	s_cselect_b32 s17, s19, s17
	s_cselect_b32 s13, s18, s13
	s_add_i32 s18, s17, 1
	s_cmp_ge_u32 s13, s12
	s_cselect_b32 s12, s18, s17
	s_xor_b32 s12, s12, s16
	s_sub_i32 s30, s12, s16
	s_lshl_b32 s16, s30, 6
	s_ashr_i32 s17, s16, 31
	v_add_lshl_u32 v2, v0, s28, 12
	v_lshl_add_u64 v[40:41], s[16:17], 2, v[2:3]
	v_lshl_add_u64 v[40:41], v[36:37], 0, v[40:41]
	v_mov_b32_e32 v51, 0
	s_lshr_b32 s18, s29, 7
.Lfnrm_loop:
	global_load_dword v80, v[40:41], off
	global_load_dword v81, v[40:41], off offset:2048
	v_lshl_add_u64 v[40:41], v[40:41], 0, s[8:9]
	global_load_dword v82, v[40:41], off
	global_load_dword v83, v[40:41], off offset:2048
	v_lshl_add_u64 v[40:41], v[40:41], 0, s[8:9]
	global_load_dword v84, v[40:41], off
	global_load_dword v85, v[40:41], off offset:2048
	v_lshl_add_u64 v[40:41], v[40:41], 0, s[8:9]
	global_load_dword v86, v[40:41], off
	global_load_dword v87, v[40:41], off offset:2048
	v_lshl_add_u64 v[40:41], v[40:41], 0, s[8:9]
	global_load_dword v88, v[40:41], off
	global_load_dword v89, v[40:41], off offset:2048
	v_lshl_add_u64 v[40:41], v[40:41], 0, s[8:9]
	global_load_dword v90, v[40:41], off
	global_load_dword v91, v[40:41], off offset:2048
	v_lshl_add_u64 v[40:41], v[40:41], 0, s[8:9]
	global_load_dword v92, v[40:41], off
	global_load_dword v93, v[40:41], off offset:2048
	v_lshl_add_u64 v[40:41], v[40:41], 0, s[8:9]
	global_load_dword v94, v[40:41], off
	global_load_dword v95, v[40:41], off offset:2048
	v_lshl_add_u64 v[40:41], v[40:41], 0, s[8:9]
	global_load_dword v96, v[40:41], off
	global_load_dword v97, v[40:41], off offset:2048
	v_lshl_add_u64 v[40:41], v[40:41], 0, s[8:9]
	global_load_dword v98, v[40:41], off
	global_load_dword v99, v[40:41], off offset:2048
	v_lshl_add_u64 v[40:41], v[40:41], 0, s[8:9]
	global_load_dword v100, v[40:41], off
	global_load_dword v101, v[40:41], off offset:2048
	v_lshl_add_u64 v[40:41], v[40:41], 0, s[8:9]
	global_load_dword v102, v[40:41], off
	global_load_dword v103, v[40:41], off offset:2048
	v_lshl_add_u64 v[40:41], v[40:41], 0, s[8:9]
	global_load_dword v104, v[40:41], off
	global_load_dword v105, v[40:41], off offset:2048
	v_lshl_add_u64 v[40:41], v[40:41], 0, s[8:9]
	global_load_dword v106, v[40:41], off
	global_load_dword v107, v[40:41], off offset:2048
	v_lshl_add_u64 v[40:41], v[40:41], 0, s[8:9]
	global_load_dword v108, v[40:41], off
	global_load_dword v109, v[40:41], off offset:2048
	v_lshl_add_u64 v[40:41], v[40:41], 0, s[8:9]
	global_load_dword v110, v[40:41], off
	global_load_dword v111, v[40:41], off offset:2048
	v_lshl_add_u64 v[40:41], v[40:41], 0, s[8:9]
	global_load_dword v112, v[40:41], off
	global_load_dword v113, v[40:41], off offset:2048
	v_lshl_add_u64 v[40:41], v[40:41], 0, s[8:9]
	global_load_dword v114, v[40:41], off
	global_load_dword v115, v[40:41], off offset:2048
	v_lshl_add_u64 v[40:41], v[40:41], 0, s[8:9]
	global_load_dword v116, v[40:41], off
	global_load_dword v117, v[40:41], off offset:2048
	v_lshl_add_u64 v[40:41], v[40:41], 0, s[8:9]
	global_load_dword v118, v[40:41], off
	global_load_dword v119, v[40:41], off offset:2048
	v_lshl_add_u64 v[40:41], v[40:41], 0, s[8:9]
	global_load_dword v120, v[40:41], off
	global_load_dword v121, v[40:41], off offset:2048
	v_lshl_add_u64 v[40:41], v[40:41], 0, s[8:9]
	global_load_dword v122, v[40:41], off
	global_load_dword v123, v[40:41], off offset:2048
	v_lshl_add_u64 v[40:41], v[40:41], 0, s[8:9]
	global_load_dword v124, v[40:41], off
	global_load_dword v125, v[40:41], off offset:2048
	v_lshl_add_u64 v[40:41], v[40:41], 0, s[8:9]
	global_load_dword v126, v[40:41], off
	global_load_dword v127, v[40:41], off offset:2048
	v_lshl_add_u64 v[40:41], v[40:41], 0, s[8:9]
	global_load_dword v128, v[40:41], off
	global_load_dword v129, v[40:41], off offset:2048
	v_lshl_add_u64 v[40:41], v[40:41], 0, s[8:9]
	global_load_dword v130, v[40:41], off
	global_load_dword v131, v[40:41], off offset:2048
	v_lshl_add_u64 v[40:41], v[40:41], 0, s[8:9]
	global_load_dword v132, v[40:41], off
	global_load_dword v133, v[40:41], off offset:2048
	v_lshl_add_u64 v[40:41], v[40:41], 0, s[8:9]
	global_load_dword v134, v[40:41], off
	global_load_dword v135, v[40:41], off offset:2048
	v_lshl_add_u64 v[40:41], v[40:41], 0, s[8:9]
	global_load_dword v136, v[40:41], off
	global_load_dword v137, v[40:41], off offset:2048
	v_lshl_add_u64 v[40:41], v[40:41], 0, s[8:9]
	global_load_dword v138, v[40:41], off
	global_load_dword v139, v[40:41], off offset:2048
	v_lshl_add_u64 v[40:41], v[40:41], 0, s[8:9]
	global_load_dword v140, v[40:41], off
	global_load_dword v141, v[40:41], off offset:2048
	v_lshl_add_u64 v[40:41], v[40:41], 0, s[8:9]
	global_load_dword v142, v[40:41], off
	global_load_dword v143, v[40:41], off offset:2048
	v_lshl_add_u64 v[40:41], v[40:41], 0, s[8:9]
	s_waitcnt vmcnt(63)
; DEV void phase_filter_norm(const Params& p, char* smem) {
;     ...
;       for (int r = ph; r < nprow; r += 4) {
;         s += part[(long)(prow0 + r) * 1024 + ct * 64 + c];
;         s += part[(long)(prow0 + r) * 1024 + 512 + ct * 64 + c];
;       }
;       red[ph * 64 + c] = s;
	v_add_f32_e32 v51, v51, v80
	s_waitcnt vmcnt(62)
	v_add_f32_e32 v51, v51, v81
	s_waitcnt vmcnt(61)
	v_add_f32_e32 v51, v51, v82
	s_waitcnt vmcnt(60)
	v_add_f32_e32 v51, v51, v83
	s_waitcnt vmcnt(59)
	v_add_f32_e32 v51, v51, v84
	s_waitcnt vmcnt(58)
	v_add_f32_e32 v51, v51, v85
	s_waitcnt vmcnt(57)
	v_add_f32_e32 v51, v51, v86
	s_waitcnt vmcnt(56)
	v_add_f32_e32 v51, v51, v87
	s_waitcnt vmcnt(55)
	v_add_f32_e32 v51, v51, v88
	s_waitcnt vmcnt(54)
	v_add_f32_e32 v51, v51, v89
	s_waitcnt vmcnt(53)
	v_add_f32_e32 v51, v51, v90
	s_waitcnt vmcnt(52)
	v_add_f32_e32 v51, v51, v91
	s_waitcnt vmcnt(51)
	v_add_f32_e32 v51, v51, v92
	s_waitcnt vmcnt(50)
	v_add_f32_e32 v51, v51, v93
	s_waitcnt vmcnt(49)
	v_add_f32_e32 v51, v51, v94
	s_waitcnt vmcnt(48)
	v_add_f32_e32 v51, v51, v95
	s_waitcnt vmcnt(47)
	v_add_f32_e32 v51, v51, v96
	s_waitcnt vmcnt(46)
	v_add_f32_e32 v51, v51, v97
	s_waitcnt vmcnt(45)
	v_add_f32_e32 v51, v51, v98
	s_waitcnt vmcnt(44)
	v_add_f32_e32 v51, v51, v99
	s_waitcnt vmcnt(43)
	v_add_f32_e32 v51, v51, v100
	s_waitcnt vmcnt(42)
	v_add_f32_e32 v51, v51, v101
	s_waitcnt vmcnt(41)
	v_add_f32_e32 v51, v51, v102
	s_waitcnt vmcnt(40)
	v_add_f32_e32 v51, v51, v103
	s_waitcnt vmcnt(39)
	v_add_f32_e32 v51, v51, v104
	s_waitcnt vmcnt(38)
	v_add_f32_e32 v51, v51, v105
	s_waitcnt vmcnt(37)
	v_add_f32_e32 v51, v51, v106
	s_waitcnt vmcnt(36)
	v_add_f32_e32 v51, v51, v107
	s_waitcnt vmcnt(35)
	v_add_f32_e32 v51, v51, v108
	s_waitcnt vmcnt(34)
	v_add_f32_e32 v51, v51, v109
	s_waitcnt vmcnt(33)
	v_add_f32_e32 v51, v51, v110
	s_waitcnt vmcnt(32)
	v_add_f32_e32 v51, v51, v111
	s_waitcnt vmcnt(31)
	v_add_f32_e32 v51, v51, v112
	s_waitcnt vmcnt(30)
	v_add_f32_e32 v51, v51, v113
	s_waitcnt vmcnt(29)
	v_add_f32_e32 v51, v51, v114
	s_waitcnt vmcnt(28)
	v_add_f32_e32 v51, v51, v115
	s_waitcnt vmcnt(27)
	v_add_f32_e32 v51, v51, v116
	s_waitcnt vmcnt(26)
	v_add_f32_e32 v51, v51, v117
	s_waitcnt vmcnt(25)
	v_add_f32_e32 v51, v51, v118
	s_waitcnt vmcnt(24)
	v_add_f32_e32 v51, v51, v119
	s_waitcnt vmcnt(23)
	v_add_f32_e32 v51, v51, v120
	s_waitcnt vmcnt(22)
	v_add_f32_e32 v51, v51, v121
	s_waitcnt vmcnt(21)
	v_add_f32_e32 v51, v51, v122
	s_waitcnt vmcnt(20)
	v_add_f32_e32 v51, v51, v123
	s_waitcnt vmcnt(19)
	v_add_f32_e32 v51, v51, v124
	s_waitcnt vmcnt(18)
	v_add_f32_e32 v51, v51, v125
	s_waitcnt vmcnt(17)
	v_add_f32_e32 v51, v51, v126
	s_waitcnt vmcnt(16)
	v_add_f32_e32 v51, v51, v127
	s_waitcnt vmcnt(15)
	v_add_f32_e32 v51, v51, v128
	s_waitcnt vmcnt(14)
	v_add_f32_e32 v51, v51, v129
	s_waitcnt vmcnt(13)
	v_add_f32_e32 v51, v51, v130
	s_waitcnt vmcnt(12)
	v_add_f32_e32 v51, v51, v131
	s_waitcnt vmcnt(11)
	v_add_f32_e32 v51, v51, v132
	s_waitcnt vmcnt(10)
	v_add_f32_e32 v51, v51, v133
	s_waitcnt vmcnt(9)
	v_add_f32_e32 v51, v51, v134
	s_waitcnt vmcnt(8)
	v_add_f32_e32 v51, v51, v135
	s_waitcnt vmcnt(7)
	v_add_f32_e32 v51, v51, v136
	s_waitcnt vmcnt(6)
	v_add_f32_e32 v51, v51, v137
	s_waitcnt vmcnt(5)
	v_add_f32_e32 v51, v51, v138
	s_waitcnt vmcnt(4)
	v_add_f32_e32 v51, v51, v139
	s_waitcnt vmcnt(3)
	v_add_f32_e32 v51, v51, v140
	s_waitcnt vmcnt(2)
	v_add_f32_e32 v51, v51, v141
	s_waitcnt vmcnt(1)
	v_add_f32_e32 v51, v51, v142
	s_waitcnt vmcnt(0)
	v_add_f32_e32 v51, v51, v143
	s_sub_u32 s18, s18, 1
	s_cmp_lg_u32 s18, 0
	s_cbranch_scc1 .Lfnrm_loop
	s_mov_b64 s[12:13], exec
